# ret_out: next item's per-head decay scalars loaded with its tile prefetch (no fresh load round trip at item start)
# baseline (speedup 1.0000x reference)
.LBB0_899:
	s_cmp_lt_i32 s92, 7
	s_cselect_b64 s[24:25], -1, 0
	s_cmp_gt_i32 s92, 6
	s_cselect_b64 s[0:1], -1, 0
	s_cmp_lt_i32 s93, 7
	s_cselect_b64 s[4:5], -1, 0
	s_or_b64 s[0:1], s[0:1], s[4:5]
	s_and_b64 vcc, exec, s[0:1]
	s_cbranch_vccnz .LBB0_905
	s_cmpk_gt_i32 s20, 0x3ff
	s_cbranch_scc1 .LBB0_905
	s_add_u32 s0, s22, 0x74bc000
	s_addc_u32 s1, s23, 0
	s_add_u32 s11, s22, 0x154bc000
	s_addc_u32 s13, s23, 0
	s_add_i32 s10, 0, 0x1b000
	s_ashr_i32 s6, s20, 7
	s_waitcnt vmcnt(0)
	v_lshrrev_b32_e32 v42, 6, v160
	s_movk_i32 s4, 0x1400
	v_mov_b32_e32 v0, s10
	s_and_b32 s16, s20, 31
	s_ashr_i32 s7, s6, 31
	v_mad_u32_u24 v73, v42, s4, v0
	s_lshl_b64 s[8:9], s[6:7], 12
	s_lshl_b32 s4, s16, 7
	s_or_b32 s8, s8, s4
	s_mul_i32 s4, s9, 0x1c00
	s_mul_hi_u32 s7, s8, 0x1c00
	s_bfe_u32 s12, s20, 0x20005
	s_add_i32 s7, s7, s4
	s_mul_i32 s4, s8, 0x1c00
	s_add_u32 s14, s0, s4
	s_addc_u32 s7, s1, s7
	s_lshl_b32 s4, s12, 8
	s_add_u32 s14, s14, s4
	s_addc_u32 s15, s7, 0
	s_lshl_b32 s6, s6, 2
	s_ashr_i32 s7, s6, 31
	s_or_b32 s6, s6, s12
	v_and_b32_e32 v162, 15, v160
	v_lshrrev_b32_e32 v164, 4, v160
	s_lshl_b64 s[6:7], s[6:7], 20
	s_add_u32 s6, s11, s6
	v_mov_b32_e32 v167, 0
	v_lshlrev_b32_e32 v166, 4, v162
	v_mul_u32_u24_e32 v68, 0xe00, v164
	s_addc_u32 s7, s13, s7
	s_lshl_b32 s12, s16, 15
	v_lshl_add_u64 v[0:1], s[14:15], 0, v[166:167]
	v_lshlrev_b32_e32 v2, 1, v68
	v_mov_b32_e32 v3, v167
	s_add_u32 s6, s6, s12
	v_lshl_add_u64 v[32:33], v[0:1], 0, v[2:3]
	s_mov_b32 s27, 0x38000
	s_addc_u32 s7, s7, 0
	v_lshlrev_b32_e32 v168, 4, v160
	v_mov_b32_e32 v169, v167
	v_add_co_u32_e32 v12, vcc, s27, v32
	v_lshl_add_u64 v[40:41], s[6:7], 0, v[168:169]
	s_nop 0
	v_addc_co_u32_e32 v13, vcc, 0, v33, vcc
	s_movk_i32 s28, 0x2000
	v_add_co_u32_e32 v16, vcc, s28, v40
	s_mov_b32 s29, 0x70000
	s_nop 0
	v_addc_co_u32_e32 v17, vcc, 0, v41, vcc
	v_add_co_u32_e32 v24, vcc, s29, v32
	s_movk_i32 s30, 0x4000
	s_nop 0
	v_addc_co_u32_e32 v25, vcc, 0, v33, vcc
	v_lshlrev_b32_e32 v70, 4, v42
	v_mov_b32_e32 v71, v167
	v_add_co_u32_e32 v28, vcc, s30, v40
	v_lshl_add_u64 v[42:43], s[8:9], 0, v[70:71]
	s_movk_i32 s26, 0x1c00
	v_addc_co_u32_e32 v29, vcc, 0, v41, vcc
	s_mov_b32 s12, 0xa8000
	v_or_b32_e32 v42, v42, v162
	v_mov_b64_e32 v[44:45], s[0:1]
	v_add_co_u32_e32 v36, vcc, s12, v32
	v_mad_u64_u32 v[44:45], s[8:9], v42, s26, v[44:45]
	s_mov_b32 s5, 0
	v_addc_co_u32_e32 v37, vcc, 0, v33, vcc
	s_movk_i32 s31, 0x6000
	v_mad_i32_i24 v45, v43, s26, v45
	v_add_co_u32_e32 v40, vcc, s31, v40
	v_lshl_add_u64 v[42:43], v[44:45], 0, s[4:5]
	v_and_b32_e32 v74, 48, v160
	v_mov_b32_e32 v75, v167
	v_addc_co_u32_e32 v41, vcc, 0, v41, vcc
	v_lshl_add_u64 v[60:61], v[42:43], 0, v[74:75]
	global_load_dwordx4 v[0:3], v[32:33], off offset:1024
	global_load_dwordx4 v[4:7], v[32:33], off offset:2048
	global_load_dwordx4 v[8:11], v[12:13], off offset:1024
	s_nop 0
	global_load_dwordx4 v[12:15], v[12:13], off offset:2048
	s_nop 0
	global_load_dwordx4 v[16:19], v[16:17], off
	s_nop 0
	global_load_dwordx4 v[20:23], v[24:25], off offset:1024
	s_nop 0
	global_load_dwordx4 v[24:27], v[24:25], off offset:2048
	s_nop 0
	global_load_dwordx4 v[28:31], v[28:29], off
	s_nop 0
	global_load_dwordx4 v[32:35], v[36:37], off offset:1024
	s_nop 0
	global_load_dwordx4 v[36:39], v[36:37], off offset:2048
	s_nop 0
	global_load_dwordx4 v[40:43], v[40:41], off
	s_nop 0
	global_load_dwordx4 v[44:47], v[60:61], off
	global_load_dwordx4 v[48:51], v[60:61], off offset:64
	global_load_dwordx4 v[52:55], v[60:61], off offset:128
	global_load_dwordx4 v[56:59], v168, s[6:7]
	s_nop 0
	global_load_dwordx4 v[60:63], v[60:61], off offset:192
	v_bfe_u32 v69, v160, 4, 2
	v_lshlrev_b32_e32 v66, 3, v160
	v_bfe_u32 v65, v160, 2, 2
	v_lshlrev_b32_e32 v72, 3, v69
	v_and_b32_e32 v71, 24, v66
	v_and_b32_e32 v67, 63, v160
	v_lshlrev_b32_e32 v64, 3, v162
	v_lshl_or_b32 v185, v69, 2, v70
	v_add_u32_e32 v77, v73, v72
	v_or_b32_e32 v65, v72, v65
	v_add_u32_e32 v73, v73, v71
	v_add_u32_e32 v79, 0, v71
	v_add_u32_e32 v80, s10, v166
	v_or_b32_e32 v170, v70, v162
	v_lshl_add_u64 v[70:71], s[22:23], 0, v[166:167]
	s_mov_b64 s[6:7], 0x30bc000
	s_movk_i32 s4, 0x130
	v_add_u32_e32 v174, 32, v164
	v_mov_b32_e32 v83, 0x2600
	v_add_u32_e32 v76, 0x200, v160
	v_or_b32_e32 v78, 0x400, v160
	v_add_u32_e32 v89, 0x600, v160
	v_add_u32_e32 v75, 0, v166
	v_add_u32_e32 v69, 0, v74
	v_mad_i32_i24 v81, v162, -14, v80
	v_lshl_add_u64 v[172:173], v[70:71], 0, s[6:7]
	v_mul_u32_u24_e32 v71, 0x110, v164
	v_mul_u32_u24_e32 v82, 0x130, v164
	v_mad_u32_u24 v84, v164, s4, v83
	v_mul_u32_u24_e32 v70, 0xe00, v174
	v_mul_u32_u24_e32 v85, 0x130, v162
	v_or_b32_e32 v180, 16, v162
	v_or_b32_e32 v182, 32, v162
	v_or_b32_e32 v184, 48, v162
	v_or_b32_e32 v186, 64, v162
	v_or_b32_e32 v188, 0x50, v162
	v_or_b32_e32 v190, 0x60, v162
	v_or_b32_e32 v192, 0x70, v162
	v_mul_u32_u24_e32 v86, 40, v162
	v_lshlrev_b32_e32 v74, 3, v76
	v_lshlrev_b32_e32 v87, 4, v76
	v_lshlrev_b32_e32 v76, 3, v78
	v_lshlrev_b32_e32 v88, 4, v78
	v_lshlrev_b32_e32 v78, 3, v89
	v_lshlrev_b32_e32 v89, 4, v89
	v_mul_u32_u24_e32 v90, 40, v65
	v_mul_u32_u24_e32 v91, 0x130, v65
	v_mad_u32_u24 v65, v65, s4, v83
	v_lshlrev_b32_e32 v187, 4, v67
	v_mul_u32_u24_e32 v67, 0x110, v174
	v_mul_u32_u24_e32 v83, 0x110, v185
	v_lshlrev_b32_e32 v166, 1, v64
	v_mbcnt_lo_u32_b32 v64, -1, 0
	v_mov_b32_e32 v171, v167
	v_or_b32_e32 v176, 64, v164
	v_add_u32_e32 v178, 0x60, v164
	v_mov_b32_e32 v179, v167
	v_mov_b32_e32 v161, v162
	v_mov_b32_e32 v163, v180
	v_mov_b32_e32 v165, v182
	v_mov_b32_e32 v169, v184
	v_mov_b32_e32 v175, v186
	v_mov_b32_e32 v177, v188
	v_mov_b32_e32 v181, v190
	v_mov_b32_e32 v183, v192
	s_mov_b32 s38, 0x3f2aaaab
	v_mov_b32_e32 v189, 0x3ecc95a3
	s_mov_b32 s39, 0x3f317218
	s_mov_b32 s40, 0xff800000
	s_mov_b32 s41, 0x33800000
	v_add_u32_e32 v191, v75, v82
	s_add_i32 s42, 0, 0x13000
	v_add_u32_e32 v193, v75, v84
	v_lshlrev_b32_e32 v194, 1, v68
	v_lshlrev_b32_e32 v196, 1, v70
	v_add_u32_e32 v204, v69, v85
	v_add_u32_e32 v205, v77, v86
	v_lshlrev_b32_e32 v198, 1, v66
	v_lshlrev_b32_e32 v206, 1, v74
	v_add_u32_e32 v207, 0, v87
	v_lshlrev_b32_e32 v208, 1, v76
	v_add_u32_e32 v209, 0, v88
	v_lshlrev_b32_e32 v210, 1, v78
	v_add_u32_e32 v211, 0, v89
	v_add_u32_e32 v212, v73, v90
	v_add_u32_e32 v213, v79, v91
	v_add_u32_e32 v214, v79, v65
	s_mov_b64 s[6:7], 0x38000
	s_mov_b64 s[8:9], 0x70000
	v_lshlrev_b32_e32 v200, 1, v72
	v_mbcnt_hi_u32_b32 v215, -1, v64
	v_add_u32_e32 v216, v81, v83
	s_brev_b32 s10, 60
	s_mov_b32 s12, 0x358637bd
	s_mov_b32 s43, 0x800000
	s_movk_i32 s44, 0x7fff
	v_mov_b32_e32 v202, 0x3f317218
	v_mov_b32_e32 v217, 0x7f800000
	v_mov_b32_e32 v218, 0x7fc00000
	v_mov_b32_e32 v219, 0xff800000
	v_add_u32_e32 v220, v80, v71
	v_add_u32_e32 v221, v80, v67
	s_mov_b32 s45, s20
	s_bfe_u32 s98, s45, 0x20005
	s_lshl_b32 s98, s98, 2
	v_mov_b32_e32 v241, s98
	global_load_dword v242, v241, s[54:55]
	global_load_dword v243, v241, s[54:55] offset:16
	s_branch .LBB0_903

.LBB0_903:
	s_bfe_u32 s4, s45, 0x20005
	s_lshl_b32 s14, s4, 2
	v_mov_b32_e32 v64, s14
	s_nop 0
	s_ashr_i32 s16, s45, 7
	s_and_b32 s47, s45, 31
	s_ashr_i32 s17, s16, 31
	s_lshl_b32 s46, s47, 7
	v_mov_b32_e32 v197, v167
	v_mov_b32_e32 v195, v167
	v_mov_b32_e32 v229, v185
	s_waitcnt vmcnt(0)
	v_mul_f32_e32 v65, 0x3fb8aa3b, v242
	v_exp_f32_e32 v68, v65
	v_mul_f32_e32 v64, 0x3fb8aa3b, v243
	v_exp_f32_e32 v98, v64
	v_sub_f32_e32 v69, 1.0, v68
	v_frexp_mant_f32_e32 v72, v69
	v_cvt_f64_f32_e32 v[64:65], v69
	v_sub_f32_e32 v70, 1.0, v98
	v_add_f32_e32 v71, -1.0, v69
	v_frexp_exp_i32_f64_e32 v64, v[64:65]
	v_cmp_gt_f32_e32 vcc, s38, v72
	v_add_f32_e32 v73, -1.0, v70
	v_frexp_mant_f32_e32 v74, v70
	v_cvt_f64_f32_e32 v[66:67], v70
	v_sub_f32_e32 v75, v71, v69
	v_subbrev_co_u32_e32 v64, vcc, 0, v64, vcc
	v_sub_f32_e64 v71, -v68, v71
	v_sub_f32_e32 v65, v73, v70
	v_frexp_exp_i32_f64_e32 v66, v[66:67]
	v_add_f32_e32 v67, 1.0, v75
	v_cmp_gt_f32_e32 vcc, s38, v74
	v_sub_f32_e64 v73, -v98, v73
	v_add_f32_e32 v65, 1.0, v65
	v_subbrev_co_u32_e32 v82, vcc, 0, v66, vcc
	v_add_f32_e32 v66, v71, v67
	v_sub_u32_e32 v67, 0, v64
	v_add_f32_e32 v65, v73, v65
	v_sub_u32_e32 v71, 0, v82
	v_ldexp_f32 v69, v69, v67
	v_ldexp_f32 v66, v66, v67
	v_ldexp_f32 v67, v70, v71
	v_ldexp_f32 v65, v65, v71
	v_add_f32_e32 v70, -1.0, v69
	v_add_f32_e32 v71, 1.0, v69
	v_add_f32_e32 v74, 1.0, v70
	v_add_f32_e32 v75, -1.0, v71
	v_add_f32_e32 v72, -1.0, v67
	v_sub_f32_e32 v74, v69, v74
	v_sub_f32_e32 v69, v69, v75
	v_add_f32_e32 v73, 1.0, v67
	v_add_f32_e32 v76, 1.0, v72
	v_add_f32_e32 v74, v66, v74
	v_add_f32_e32 v66, v66, v69
	v_add_f32_e32 v77, -1.0, v73
	v_sub_f32_e32 v75, v67, v76
	v_add_f32_e32 v76, v71, v66
	v_sub_f32_e32 v67, v67, v77
	v_rcp_f32_e32 v77, v76
	v_add_f32_e32 v75, v65, v75
	v_add_f32_e32 v65, v65, v67
	v_add_f32_e32 v83, v73, v65
	v_add_f32_e32 v67, v70, v74
	v_sub_f32_e32 v73, v83, v73
	v_add_f32_e32 v69, v72, v75
	v_sub_f32_e32 v70, v67, v70
	v_sub_f32_e32 v85, v65, v73
	v_mul_f32_e32 v65, v67, v77
	v_sub_f32_e32 v71, v76, v71
	v_sub_f32_e32 v72, v69, v72
	v_sub_f32_e32 v74, v74, v70
	v_mul_f32_e32 v70, v76, v65
	v_sub_f32_e32 v78, v66, v71
	v_sub_f32_e32 v86, v75, v72
	v_fma_f32 v72, v65, v76, -v70
	v_fmac_f32_e32 v72, v65, v78
	v_add_f32_e32 v66, v70, v72
	v_sub_f32_e32 v71, v67, v66
	v_mov_b32_e32 v73, v66
	v_pk_add_f32 v[66:67], v[66:67], v[70:71] neg_lo:[0,1] neg_hi:[0,1]
	v_cvt_f32_i32_e32 v64, v64
	v_pk_add_f32 v[66:67], v[66:67], v[72:73] neg_lo:[0,1] neg_hi:[0,1]
	v_rcp_f32_e32 v84, v83
	v_add_f32_e32 v67, v74, v67
	v_add_f32_e32 v66, v66, v67
	v_add_f32_e32 v67, v71, v66
	v_mul_f32_e32 v73, v77, v67
	v_mul_f32_e32 v70, v76, v73
	v_fma_f32 v72, v73, v76, -v70
	v_sub_f32_e32 v71, v71, v67
	v_fmac_f32_e32 v72, v73, v78
	v_add_f32_e32 v74, v66, v71
	v_add_f32_e32 v75, v65, v73
	v_add_f32_e32 v66, v70, v72
	v_sub_f32_e32 v65, v75, v65
	v_sub_f32_e32 v71, v67, v66
	v_sub_f32_e32 v65, v73, v65
	v_mov_b32_e32 v73, v66
	v_pk_add_f32 v[66:67], v[66:67], v[70:71] neg_lo:[0,1] neg_hi:[0,1]
	v_cmp_neq_f32_e32 vcc, s40, v68
	v_pk_add_f32 v[66:67], v[66:67], v[72:73] neg_lo:[0,1] neg_hi:[0,1]
	v_mul_f32_e32 v87, v69, v84
	v_add_f32_e32 v67, v74, v67
	v_add_f32_e32 v66, v66, v67
	v_add_f32_e32 v66, v71, v66
	v_mul_f32_e32 v66, v77, v66
	v_add_f32_e32 v65, v65, v66
	v_add_f32_e32 v66, v75, v65
	v_mul_f32_e32 v70, v66, v66
	v_sub_f32_e32 v71, v66, v75
	v_fmamk_f32 v72, v70, 0x3e9b6dac, v189
	v_sub_f32_e32 v71, v65, v71
	v_mul_f32_e32 v65, v66, v70
	v_fmaak_f32 v203, v70, v72, 0x3f2aaada
	v_ldexp_f32 v73, v71, 1
	v_pk_mul_f32 v[70:71], v[64:65], v[202:203]
	v_ldexp_f32 v67, v66, 1
	v_fma_f32 v66, v64, s39, -v70
	v_fmac_f32_e32 v66, 0xb102e308, v64
	v_pk_add_f32 v[64:65], v[70:71], v[66:67]
	v_mov_b32_e32 v72, v70
	v_sub_f32_e32 v76, v65, v67
	v_pk_add_f32 v[74:75], v[64:65], v[70:71] neg_lo:[0,1] neg_hi:[0,1]
	v_sub_f32_e32 v71, v71, v76
	v_add_f32_e32 v73, v73, v71
	v_pk_add_f32 v[78:79], v[64:65], v[72:73]
	v_mov_b32_e32 v67, v64
	v_mov_b32_e32 v75, v79
	v_pk_add_f32 v[80:81], v[66:67], v[74:75] neg_lo:[0,1] neg_hi:[0,1]
	v_pk_add_f32 v[66:67], v[66:67], v[74:75]
	v_mov_b32_e32 v70, v65
	v_mov_b32_e32 v77, v64
	v_pk_add_f32 v[64:65], v[66:67], v[64:65] op_sel:[1,0] op_sel_hi:[0,1] neg_lo:[0,1] neg_hi:[0,1]
	v_mov_b32_e32 v76, v73
	v_mov_b32_e32 v72, v79
	v_mov_b32_e32 v73, v67
	v_mov_b32_e32 v71, v64
	v_pk_add_f32 v[74:75], v[78:79], v[64:65] op_sel_hi:[1,0] neg_lo:[0,1] neg_hi:[0,1]
	v_pk_add_f32 v[64:65], v[72:73], v[70:71] neg_lo:[0,1] neg_hi:[0,1]
	v_mov_b32_e32 v74, v80
	v_pk_add_f32 v[64:65], v[76:77], v[64:65] neg_lo:[0,1] neg_hi:[0,1]
	v_mov_b32_e32 v81, v67
	v_pk_add_f32 v[70:71], v[74:75], v[64:65]
	v_cmp_lt_f32_e64 s[14:15], |v68|, s41
	v_pk_add_f32 v[72:73], v[70:71], v[70:71] op_sel:[0,1] op_sel_hi:[1,0]
	s_nop 0
	v_pk_add_f32 v[66:67], v[66:67], v[72:73] op_sel:[1,0] op_sel_hi:[0,1]
	v_mov_b32_e32 v71, v66
	v_mov_b32_e32 v65, v72
	v_pk_add_f32 v[72:73], v[70:71], v[80:81] neg_lo:[0,1] neg_hi:[0,1]
	s_nop 0
	v_sub_f32_e32 v67, v70, v72
	v_pk_add_f32 v[64:65], v[64:65], v[72:73] neg_lo:[0,1] neg_hi:[0,1]
	v_sub_f32_e32 v67, v80, v67
	v_add_f32_e32 v64, v64, v67
	v_add_f32_e32 v64, v64, v65
	v_add_f32_e32 v64, v66, v64
	v_cndmask_b32_e32 v64, v217, v64, vcc
	v_cmp_nlt_f32_e32 vcc, 1.0, v68
	s_nop 1
	v_cndmask_b32_e32 v64, v218, v64, vcc
	v_cmp_neq_f32_e32 vcc, 1.0, v68
	s_nop 1
	v_cndmask_b32_e32 v64, v219, v64, vcc
	v_cndmask_b32_e64 v99, v64, -v68, s[14:15]
	v_mul_f32_e32 v64, v83, v87
	v_fma_f32 v66, v87, v83, -v64
	v_fmac_f32_e32 v66, v87, v85
	v_add_f32_e32 v68, v64, v66
	v_sub_f32_e32 v65, v69, v68
	v_pk_add_f32 v[70:71], v[68:69], v[64:65] neg_lo:[0,1] neg_hi:[0,1]
	v_mov_b32_e32 v67, v68
	v_pk_add_f32 v[66:67], v[70:71], v[66:67] neg_lo:[0,1] neg_hi:[0,1]
	s_lshl_b64 s[14:15], s[16:17], 12
	v_add_f32_e32 v64, v86, v67
	v_add_f32_e32 v66, v66, v64
	v_add_f32_e32 v67, v65, v66
	v_mul_f32_e32 v72, v84, v67
	v_mul_f32_e32 v64, v83, v72
	v_fma_f32 v68, v72, v83, -v64
	v_fmac_f32_e32 v68, v72, v85
	v_sub_f32_e32 v65, v65, v67
	v_add_f32_e32 v73, v66, v65
	v_add_f32_e32 v66, v64, v68
	v_sub_f32_e32 v65, v67, v66
	v_pk_add_f32 v[70:71], v[66:67], v[64:65] neg_lo:[0,1] neg_hi:[0,1]
	v_mov_b32_e32 v69, v66
	v_pk_add_f32 v[66:67], v[70:71], v[68:69] neg_lo:[0,1] neg_hi:[0,1]
	s_or_b32 s14, s14, s46
	v_add_f32_e32 v64, v73, v67
	v_add_f32_e32 v64, v66, v64
	v_add_f32_e32 v64, v65, v64
	v_add_f32_e32 v65, v87, v72
	v_sub_f32_e32 v66, v65, v87
	v_mul_f32_e32 v64, v84, v64
	v_sub_f32_e32 v66, v72, v66
	v_add_f32_e32 v66, v66, v64
	v_add_f32_e32 v67, v65, v66
	v_mul_f32_e32 v68, v67, v67
	v_fmamk_f32 v64, v68, 0x3e9b6dac, v189
	v_fmaak_f32 v203, v68, v64, 0x3f2aaada
	v_cvt_f32_i32_e32 v64, v82
	v_sub_f32_e32 v65, v67, v65
	v_sub_f32_e32 v65, v66, v65
	v_ldexp_f32 v86, v65, 1
	v_mul_f32_e32 v65, v67, v68
	s_mul_i32 s17, s15, 0x1c00
	s_mul_hi_u32 s46, s14, 0x1c00
	v_pk_mul_f32 v[82:83], v[64:65], v[202:203]
	s_add_i32 s46, s46, s17
	s_mul_i32 s17, s14, 0x1c00
	v_fma_f32 v80, v64, s39, -v82
	s_add_u32 s17, s0, s17
	v_ldexp_f32 v81, v67, 1
	v_fmac_f32_e32 v80, 0xb102e308, v64
	s_addc_u32 s49, s1, s46
	s_lshl_b32 s46, s4, 7
	s_lshl_b32 s48, s4, 8
	v_pk_add_f32 v[84:85], v[82:83], v[80:81]
	s_add_u32 s48, s17, s48
	v_sub_f32_e32 v64, v85, v81
	s_addc_u32 s49, s49, 0
	v_sub_f32_e32 v81, v83, v64
	v_lshl_add_u64 v[64:65], s[48:49], 0, v[166:167]
	v_lshl_add_u64 v[72:73], v[64:65], 0, v[196:197]
	v_add_co_u32_e32 v74, vcc, s27, v72
	v_or_b32_e32 v87, s46, v162
	s_nop 0
	v_addc_co_u32_e32 v75, vcc, 0, v73, vcc
	v_add_co_u32_e32 v76, vcc, s29, v72
	v_lshl_add_u64 v[66:67], v[64:65], 0, v[194:195]
	s_nop 0
	v_addc_co_u32_e32 v77, vcc, 0, v73, vcc
	v_lshlrev_b32_e32 v87, 2, v87
	global_load_dwordx4 v[64:67], v[66:67], off offset:3072
	s_nop 0
	global_load_dwordx4 v[68:71], v[72:73], off offset:3072
	s_nop 0
	global_load_dwordx4 v[72:75], v[74:75], off offset:3072
	s_nop 0
	global_load_dwordx4 v[76:79], v[76:77], off offset:3072
	s_nop 0
	global_load_dword v228, v87, s[56:57]
	global_load_dword v227, v87, s[56:57] offset:64
	global_load_dword v226, v87, s[56:57] offset:128
	global_load_dword v225, v87, s[56:57] offset:192
	global_load_dword v224, v87, s[56:57] offset:256
	global_load_dword v223, v87, s[56:57] offset:320
	global_load_dword v222, v87, s[56:57] offset:384
	global_load_dword v203, v87, s[56:57] offset:448
	v_add_f32_e32 v87, v86, v81
	v_mov_b32_e32 v86, v82
	v_pk_add_f32 v[82:83], v[84:85], v[82:83] neg_lo:[0,1] neg_hi:[0,1]
	v_pk_add_f32 v[88:89], v[84:85], v[86:87]
	v_mov_b32_e32 v81, v84
	v_mov_b32_e32 v83, v89
	v_pk_add_f32 v[92:93], v[80:81], v[82:83] neg_lo:[0,1] neg_hi:[0,1]
	v_pk_add_f32 v[80:81], v[80:81], v[82:83]
	v_mov_b32_e32 v94, v85
	v_pk_add_f32 v[82:83], v[80:81], v[84:85] op_sel:[1,0] op_sel_hi:[0,1] neg_lo:[0,1] neg_hi:[0,1]
	v_pk_add_f32 v[90:91], v[88:89], v[82:83] op_sel_hi:[1,0] neg_lo:[0,1] neg_hi:[0,1]
	v_mov_b32_e32 v88, v89
	v_mov_b32_e32 v89, v81
	v_mov_b32_e32 v95, v82
	v_pk_add_f32 v[82:83], v[88:89], v[94:95] neg_lo:[0,1] neg_hi:[0,1]
	v_mov_b32_e32 v86, v87
	v_mov_b32_e32 v87, v84
	v_pk_add_f32 v[84:85], v[86:87], v[82:83] neg_lo:[0,1] neg_hi:[0,1]
	v_mov_b32_e32 v90, v92
	v_pk_add_f32 v[88:89], v[90:91], v[84:85]
	ds_write_b128 v191, v[0:3]
	ds_write_b128 v191, v[4:7] offset:38912
	v_pk_add_f32 v[86:87], v[88:89], v[88:89] op_sel:[0,1] op_sel_hi:[1,0]
	v_mov_b32_e32 v93, v81
	v_pk_add_f32 v[94:95], v[80:81], v[86:87] op_sel:[1,0] op_sel_hi:[0,1]
	v_add_u32_e32 v80, s42, v168
	ds_write_b128 v80, v[56:59]
	ds_write_b128 v191, v[8:11] offset:9728
	ds_write_b128 v191, v[12:15] offset:48640
	ds_write_b128 v80, v[16:19] offset:8192
	ds_write_b128 v191, v[20:23] offset:19456
	ds_write_b128 v191, v[24:27] offset:58368
	ds_write_b128 v80, v[28:31] offset:16384
	ds_write_b128 v191, v[32:35] offset:29184
	ds_write_b128 v193, v[36:39] offset:58368
	ds_write_b128 v80, v[40:43] offset:24576
	s_waitcnt lgkmcnt(0)
	s_barrier
	ds_read_b128 v[80:83], v204
	v_mov_b32_e32 v89, v94
	v_pk_add_f32 v[90:91], v[88:89], v[92:93] neg_lo:[0,1] neg_hi:[0,1]
	v_mov_b32_e32 v85, v86
	v_pk_add_f32 v[96:97], v[84:85], v[90:91] neg_lo:[0,1] neg_hi:[0,1]
	ds_read_b128 v[84:87], v204 offset:64
	s_waitcnt lgkmcnt(0)
	v_mfma_f32_16x16x32_bf16 v[80:83], v[44:47], v[80:83], 0
	v_sub_f32_e32 v93, v88, v90
	ds_read_b128 v[88:91], v204 offset:128
	v_cmp_neq_f32_e32 vcc, s40, v98
	v_mfma_f32_16x16x32_bf16 v[80:83], v[48:51], v[84:87], v[80:83]
	v_sub_f32_e32 v84, v92, v93
	v_add_f32_e32 v92, v96, v84
	ds_read_b128 v[84:87], v204 offset:192
	s_waitcnt lgkmcnt(1)
	v_mfma_f32_16x16x32_bf16 v[80:83], v[52:55], v[88:91], v[80:83]
	v_add_f32_e32 v88, v92, v97
	v_add_f32_e32 v92, v94, v88
	ds_read_b128 v[88:91], v204 offset:4864
	s_waitcnt lgkmcnt(1)
	v_mfma_f32_16x16x32_bf16 v[100:103], v[60:63], v[84:87], v[80:83]
	v_cndmask_b32_e32 v92, v217, v92, vcc
	v_cmp_nlt_f32_e32 vcc, 1.0, v98
	v_cmp_lt_f32_e64 s[48:49], |v98|, s41
	ds_read_b128 v[80:83], v204 offset:4928
	s_waitcnt lgkmcnt(1)
	v_mfma_f32_16x16x32_bf16 v[84:87], v[44:47], v[88:91], 0
	ds_read_b128 v[88:91], v204 offset:4992
	v_cndmask_b32_e32 v92, v218, v92, vcc
	v_cmp_neq_f32_e32 vcc, 1.0, v98
	s_waitcnt lgkmcnt(1)
	v_mfma_f32_16x16x32_bf16 v[80:83], v[48:51], v[80:83], v[84:87]
	v_mul_f32_e32 v230, 0x3fb8aa3b, v99
	v_cndmask_b32_e32 v92, v219, v92, vcc
	v_cndmask_b32_e64 v120, v92, -v98, s[48:49]
	ds_read_b128 v[84:87], v204 offset:5056
	s_waitcnt lgkmcnt(1)
	v_mfma_f32_16x16x32_bf16 v[80:83], v[52:55], v[88:91], v[80:83]
	s_lshl_b32 s16, s16, 2
	s_waitcnt lgkmcnt(0)
	v_mfma_f32_16x16x32_bf16 v[104:107], v[60:63], v[84:87], v[80:83]
	s_nop 4
	ds_read_b128 v[80:83], v204 offset:9728
	ds_read_b128 v[84:87], v204 offset:9792
	s_waitcnt lgkmcnt(1)
	v_mfma_f32_16x16x32_bf16 v[80:83], v[44:47], v[80:83], 0
	s_waitcnt lgkmcnt(0)
	v_mfma_f32_16x16x32_bf16 v[80:83], v[48:51], v[84:87], v[80:83]
	ds_read_b128 v[84:87], v204 offset:9856
	ds_read_b128 v[88:91], v204 offset:9920
	s_waitcnt lgkmcnt(1)
	v_mfma_f32_16x16x32_bf16 v[80:83], v[52:55], v[84:87], v[80:83]
	s_waitcnt lgkmcnt(0)
	v_mfma_f32_16x16x32_bf16 v[108:111], v[60:63], v[88:91], v[80:83]
	s_nop 5
	ds_read_b128 v[80:83], v204 offset:14592
	ds_read_b128 v[84:87], v204 offset:14656
	s_waitcnt lgkmcnt(1)
	v_mfma_f32_16x16x32_bf16 v[80:83], v[44:47], v[80:83], 0
	s_waitcnt lgkmcnt(0)
	v_mfma_f32_16x16x32_bf16 v[80:83], v[48:51], v[84:87], v[80:83]
	ds_read_b128 v[84:87], v204 offset:14720
	ds_read_b128 v[88:91], v204 offset:14784
	s_waitcnt lgkmcnt(1)
	v_mfma_f32_16x16x32_bf16 v[80:83], v[52:55], v[84:87], v[80:83]
	s_waitcnt lgkmcnt(0)
	v_mfma_f32_16x16x32_bf16 v[96:99], v[60:63], v[88:91], v[80:83]
	s_nop 5
	ds_read_b128 v[80:83], v204 offset:19456
	ds_read_b128 v[84:87], v204 offset:19520
	s_waitcnt lgkmcnt(1)
	v_mfma_f32_16x16x32_bf16 v[80:83], v[44:47], v[80:83], 0
	s_waitcnt lgkmcnt(0)
	v_mfma_f32_16x16x32_bf16 v[80:83], v[48:51], v[84:87], v[80:83]
	ds_read_b128 v[84:87], v204 offset:19584
	ds_read_b128 v[88:91], v204 offset:19648
	s_waitcnt lgkmcnt(1)
	v_mfma_f32_16x16x32_bf16 v[80:83], v[52:55], v[84:87], v[80:83]
	s_waitcnt lgkmcnt(0)
	v_mfma_f32_16x16x32_bf16 v[92:95], v[60:63], v[88:91], v[80:83]
	s_nop 5
	ds_read_b128 v[80:83], v204 offset:24320
	ds_read_b128 v[84:87], v204 offset:24384
	s_waitcnt lgkmcnt(1)
	v_mfma_f32_16x16x32_bf16 v[80:83], v[44:47], v[80:83], 0
	s_waitcnt lgkmcnt(0)
	v_mfma_f32_16x16x32_bf16 v[80:83], v[48:51], v[84:87], v[80:83]
	ds_read_b128 v[84:87], v204 offset:24448
	ds_read_b128 v[88:91], v204 offset:24512
	s_waitcnt lgkmcnt(1)
	v_mfma_f32_16x16x32_bf16 v[80:83], v[52:55], v[84:87], v[80:83]
	s_waitcnt lgkmcnt(0)
	v_mfma_f32_16x16x32_bf16 v[88:91], v[60:63], v[88:91], v[80:83]
	s_nop 5
	ds_read_b128 v[80:83], v204 offset:29184
	ds_read_b128 v[84:87], v204 offset:29248
	s_waitcnt lgkmcnt(1)
	v_mfma_f32_16x16x32_bf16 v[80:83], v[44:47], v[80:83], 0
	s_waitcnt lgkmcnt(0)
	v_mfma_f32_16x16x32_bf16 v[80:83], v[48:51], v[84:87], v[80:83]
	ds_read_b128 v[84:87], v204 offset:29312
	ds_read_b128 v[112:115], v204 offset:29376
	s_waitcnt lgkmcnt(1)
	v_mfma_f32_16x16x32_bf16 v[80:83], v[52:55], v[84:87], v[80:83]
	s_waitcnt lgkmcnt(0)
	v_mfma_f32_16x16x32_bf16 v[84:87], v[60:63], v[112:115], v[80:83]
	s_nop 5
	ds_read_b128 v[80:83], v204 offset:34048
	ds_read_b128 v[112:115], v204 offset:34112
	s_waitcnt lgkmcnt(1)
	v_mfma_f32_16x16x32_bf16 v[80:83], v[44:47], v[80:83], 0
	s_waitcnt lgkmcnt(0)
	v_mfma_f32_16x16x32_bf16 v[80:83], v[48:51], v[112:115], v[80:83]
	ds_read_b128 v[112:115], v204 offset:34176
	ds_read_b128 v[116:119], v204 offset:34240
	s_waitcnt lgkmcnt(1)
	v_mfma_f32_16x16x32_bf16 v[80:83], v[52:55], v[112:115], v[80:83]
	s_waitcnt lgkmcnt(0)
	v_mfma_f32_16x16x32_bf16 v[80:83], v[60:63], v[116:119], v[80:83]
	v_add_u32_e32 v232, 1, v229
	v_sub_u32_e32 v114, v232, v162
	v_sub_u32_e32 v112, v229, v162
	v_cvt_f32_i32_e32 v115, v114
	v_mul_f32_e32 v231, 0x3fb8aa3b, v120
	v_cmp_lt_i32_e32 vcc, 0, v112
	v_cvt_f32_i32_e32 v112, v112
	v_add_u32_e32 v233, 3, v229
	v_cndmask_b32_e64 v113, -v231, v230, vcc
	v_cmp_lt_i32_e32 vcc, 0, v114
	v_mul_f32_e32 v112, v113, v112
	v_exp_f32_e32 v112, v112
	v_cndmask_b32_e64 v114, -v231, v230, vcc
	v_mul_f32_e32 v114, v114, v115
	v_exp_f32_e32 v114, v114
	v_cmp_ne_u32_e32 vcc, v232, v161
	v_add_u32_e32 v234, 2, v229
	s_or_b32 s4, s16, s4
	v_cndmask_b32_e32 v113, 2.0, v114, vcc
	v_cmp_ne_u32_e32 vcc, v229, v162
	v_sub_u32_e32 v114, v233, v162
	v_cvt_f32_i32_e32 v115, v114
	v_cndmask_b32_e32 v112, 2.0, v112, vcc
	v_pk_mul_f32 v[100:101], v[100:101], v[112:113]
	v_sub_u32_e32 v112, v234, v162
	v_cmp_lt_i32_e32 vcc, 0, v112
	v_cvt_f32_i32_e32 v112, v112
	v_cvt_pk_bf16_f32 v100, v100, v101
	v_cndmask_b32_e64 v113, -v231, v230, vcc
	v_cmp_lt_i32_e32 vcc, 0, v114
	v_mul_f32_e32 v112, v113, v112
	v_exp_f32_e32 v112, v112
	v_cndmask_b32_e64 v114, -v231, v230, vcc
	v_mul_f32_e32 v114, v114, v115
	v_exp_f32_e32 v114, v114
	v_cmp_ne_u32_e32 vcc, v233, v161
	s_add_i32 s16, s4, 32
	s_ashr_i32 s17, s16, 31
	v_cndmask_b32_e32 v113, 2.0, v114, vcc
	v_cmp_ne_u32_e32 vcc, v234, v162
	s_lshl_b64 s[16:17], s[16:17], 20
	s_add_u32 s4, s11, s16
	v_cndmask_b32_e32 v112, 2.0, v112, vcc
	v_pk_mul_f32 v[102:103], v[102:103], v[112:113]
	v_sub_u32_e32 v112, v232, v180
	v_cvt_pk_bf16_f32 v101, v102, v103
	v_sub_u32_e32 v102, v229, v180
	v_cvt_f32_i32_e32 v113, v112
	v_cmp_lt_i32_e32 vcc, 0, v102
	v_cvt_f32_i32_e32 v102, v102
	s_addc_u32 s17, s13, s17
	v_cndmask_b32_e64 v103, -v231, v230, vcc
	v_cmp_lt_i32_e32 vcc, 0, v112
	v_mul_f32_e32 v102, v103, v102
	v_exp_f32_e32 v102, v102
	v_cndmask_b32_e64 v112, -v231, v230, vcc
	v_mul_f32_e32 v112, v112, v113
	v_exp_f32_e32 v112, v112
	v_cmp_ne_u32_e32 vcc, v232, v163
	s_lshl_b32 s16, s47, 15
	s_add_u32 s16, s4, s16
	v_cndmask_b32_e32 v103, 2.0, v112, vcc
	v_cmp_ne_u32_e32 vcc, v229, v180
	v_sub_u32_e32 v112, v233, v180
	v_cvt_f32_i32_e32 v113, v112
	v_cndmask_b32_e32 v102, 2.0, v102, vcc
	v_pk_mul_f32 v[102:103], v[104:105], v[102:103]
	v_sub_u32_e32 v104, v234, v180
	v_cmp_lt_i32_e32 vcc, 0, v104
	v_cvt_f32_i32_e32 v104, v104
	v_cvt_pk_bf16_f32 v102, v102, v103
	v_cndmask_b32_e64 v105, -v231, v230, vcc
	v_cmp_lt_i32_e32 vcc, 0, v112
	v_mul_f32_e32 v104, v105, v104
	v_exp_f32_e32 v104, v104
	v_cndmask_b32_e64 v112, -v231, v230, vcc
	v_mul_f32_e32 v112, v112, v113
	v_exp_f32_e32 v112, v112
	v_cmp_ne_u32_e32 vcc, v233, v163
	s_addc_u32 s17, s17, 0
	global_load_dwordx4 v[0:3], v198, s[16:17]
	global_load_dwordx4 v[4:7], v206, s[16:17]
	global_load_dwordx4 v[8:11], v208, s[16:17]
	global_load_dwordx4 v[12:15], v210, s[16:17]
	s_nop 0
	v_cndmask_b32_e32 v105, 2.0, v112, vcc
	v_cmp_ne_u32_e32 vcc, v234, v180
	s_nop 1
	v_cndmask_b32_e32 v104, 2.0, v104, vcc
	v_pk_mul_f32 v[104:105], v[106:107], v[104:105]
	s_nop 0
	v_cvt_pk_bf16_f32 v103, v104, v105
	ds_write2_b64 v205, v[100:101], v[102:103] offset1:80
	v_sub_u32_e32 v102, v232, v182
	v_sub_u32_e32 v100, v229, v182
	v_cvt_f32_i32_e32 v103, v102
	v_cmp_lt_i32_e32 vcc, 0, v100
	v_cvt_f32_i32_e32 v100, v100
	v_sub_u32_e32 v104, v233, v182
	v_cndmask_b32_e64 v101, -v231, v230, vcc
	v_cmp_lt_i32_e32 vcc, 0, v102
	v_mul_f32_e32 v100, v101, v100
	v_exp_f32_e32 v100, v100
	v_cndmask_b32_e64 v102, -v231, v230, vcc
	v_mul_f32_e32 v102, v102, v103
	v_exp_f32_e32 v102, v102
	v_cmp_ne_u32_e32 vcc, v232, v165
	v_cvt_f32_i32_e32 v105, v104
	s_nop 0
	v_cndmask_b32_e32 v101, 2.0, v102, vcc
	v_cmp_ne_u32_e32 vcc, v229, v182
	v_sub_u32_e32 v102, v234, v182
	s_nop 0
	v_cndmask_b32_e32 v100, 2.0, v100, vcc
	v_cmp_lt_i32_e32 vcc, 0, v102
	v_cvt_f32_i32_e32 v102, v102
	v_pk_mul_f32 v[100:101], v[108:109], v[100:101]
	v_cndmask_b32_e64 v103, -v231, v230, vcc
	v_cmp_lt_i32_e32 vcc, 0, v104
	v_mul_f32_e32 v102, v103, v102
	v_exp_f32_e32 v102, v102
	v_cndmask_b32_e64 v104, -v231, v230, vcc
	v_mul_f32_e32 v104, v104, v105
	v_exp_f32_e32 v104, v104
	v_cmp_ne_u32_e32 vcc, v233, v165
	v_cvt_pk_bf16_f32 v100, v100, v101
	s_nop 0
	v_cndmask_b32_e32 v103, 2.0, v104, vcc
	v_cmp_ne_u32_e32 vcc, v234, v182
	v_sub_u32_e32 v104, v232, v184
	v_cvt_f32_i32_e32 v105, v104
	v_cndmask_b32_e32 v102, 2.0, v102, vcc
	v_pk_mul_f32 v[102:103], v[110:111], v[102:103]
	s_nop 0
	v_cvt_pk_bf16_f32 v101, v102, v103
	v_sub_u32_e32 v102, v229, v184
	v_cmp_lt_i32_e32 vcc, 0, v102
	v_cvt_f32_i32_e32 v102, v102
	s_nop 0
	v_cndmask_b32_e64 v103, -v231, v230, vcc
	v_cmp_lt_i32_e32 vcc, 0, v104
	v_mul_f32_e32 v102, v103, v102
	v_exp_f32_e32 v102, v102
	v_cndmask_b32_e64 v104, -v231, v230, vcc
	v_mul_f32_e32 v104, v104, v105
	v_exp_f32_e32 v104, v104
	v_cmp_ne_u32_e32 vcc, v232, v169
	s_nop 1
	v_cndmask_b32_e32 v103, 2.0, v104, vcc
	v_cmp_ne_u32_e32 vcc, v229, v184
	v_sub_u32_e32 v104, v233, v184
	v_cvt_f32_i32_e32 v105, v104
	v_cndmask_b32_e32 v102, 2.0, v102, vcc
	v_pk_mul_f32 v[96:97], v[96:97], v[102:103]
	v_sub_u32_e32 v102, v234, v184
	v_cmp_lt_i32_e32 vcc, 0, v102
	v_cvt_f32_i32_e32 v102, v102
	v_cvt_pk_bf16_f32 v96, v96, v97
	v_cndmask_b32_e64 v103, -v231, v230, vcc
	v_cmp_lt_i32_e32 vcc, 0, v104
	v_mul_f32_e32 v102, v103, v102
	v_exp_f32_e32 v102, v102
	v_cndmask_b32_e64 v104, -v231, v230, vcc
	v_mul_f32_e32 v104, v104, v105
	v_exp_f32_e32 v104, v104
	v_cmp_ne_u32_e32 vcc, v233, v169
	s_nop 1
	v_cndmask_b32_e32 v103, 2.0, v104, vcc
	v_cmp_ne_u32_e32 vcc, v234, v184
	s_nop 1
	v_cndmask_b32_e32 v102, 2.0, v102, vcc
	v_pk_mul_f32 v[98:99], v[98:99], v[102:103]
	s_nop 0
	v_cvt_pk_bf16_f32 v97, v98, v99
	v_sub_u32_e32 v98, v232, v186
	ds_write2_b64 v205, v[100:101], v[96:97] offset0:160 offset1:240
	v_sub_u32_e32 v96, v229, v186
	v_cvt_f32_i32_e32 v99, v98
	v_cmp_lt_i32_e32 vcc, 0, v96
	v_cvt_f32_i32_e32 v96, v96
	s_nop 0
	v_cndmask_b32_e64 v97, -v231, v230, vcc
	v_cmp_lt_i32_e32 vcc, 0, v98
	v_mul_f32_e32 v96, v97, v96
	v_exp_f32_e32 v96, v96
	v_cndmask_b32_e64 v98, -v231, v230, vcc
	v_mul_f32_e32 v98, v98, v99
	v_exp_f32_e32 v98, v98
	v_cmp_ne_u32_e32 vcc, v232, v175
	s_nop 1
	v_cndmask_b32_e32 v97, 2.0, v98, vcc
	v_cmp_ne_u32_e32 vcc, v229, v186
	v_sub_u32_e32 v98, v233, v186
	v_cvt_f32_i32_e32 v99, v98
	v_cndmask_b32_e32 v96, 2.0, v96, vcc
	v_pk_mul_f32 v[92:93], v[96:97], v[92:93]
	v_sub_u32_e32 v96, v234, v186
	v_cmp_lt_i32_e32 vcc, 0, v96
	v_cvt_f32_i32_e32 v96, v96
	v_cvt_pk_bf16_f32 v92, v92, v93
	v_cndmask_b32_e64 v97, -v231, v230, vcc
	v_cmp_lt_i32_e32 vcc, 0, v98
	v_mul_f32_e32 v96, v97, v96
	v_exp_f32_e32 v96, v96
	v_cndmask_b32_e64 v98, -v231, v230, vcc
	v_mul_f32_e32 v98, v98, v99
	v_exp_f32_e32 v98, v98
	v_cmp_ne_u32_e32 vcc, v233, v175
	s_nop 1
	v_cndmask_b32_e32 v97, 2.0, v98, vcc
	v_cmp_ne_u32_e32 vcc, v234, v186
	s_nop 1
	v_cndmask_b32_e32 v96, 2.0, v96, vcc
	v_pk_mul_f32 v[94:95], v[96:97], v[94:95]
	v_sub_u32_e32 v96, v232, v188
	v_cvt_pk_bf16_f32 v93, v94, v95
	v_sub_u32_e32 v94, v229, v188
	v_cvt_f32_i32_e32 v97, v96
	v_cmp_lt_i32_e32 vcc, 0, v94
	v_cvt_f32_i32_e32 v94, v94
	s_nop 0
	v_cndmask_b32_e64 v95, -v231, v230, vcc
	v_cmp_lt_i32_e32 vcc, 0, v96
	v_mul_f32_e32 v94, v95, v94
	v_exp_f32_e32 v94, v94
	v_cndmask_b32_e64 v96, -v231, v230, vcc
	v_mul_f32_e32 v96, v96, v97
	v_exp_f32_e32 v96, v96
	v_cmp_ne_u32_e32 vcc, v232, v177
	s_nop 1
	v_cndmask_b32_e32 v95, 2.0, v96, vcc
	v_cmp_ne_u32_e32 vcc, v229, v188
	v_sub_u32_e32 v96, v233, v188
	v_cvt_f32_i32_e32 v97, v96
	v_cndmask_b32_e32 v94, 2.0, v94, vcc
	v_pk_mul_f32 v[88:89], v[94:95], v[88:89]
	v_sub_u32_e32 v94, v234, v188
	v_cmp_lt_i32_e32 vcc, 0, v94
	v_cvt_f32_i32_e32 v94, v94
	v_cvt_pk_bf16_f32 v88, v88, v89
	v_cndmask_b32_e64 v95, -v231, v230, vcc
	v_cmp_lt_i32_e32 vcc, 0, v96
	v_mul_f32_e32 v94, v95, v94
	v_exp_f32_e32 v94, v94
	v_cndmask_b32_e64 v96, -v231, v230, vcc
	v_mul_f32_e32 v96, v96, v97
	v_exp_f32_e32 v96, v96
	v_cmp_ne_u32_e32 vcc, v233, v177
	s_nop 1
	v_cndmask_b32_e32 v95, 2.0, v96, vcc
	v_cmp_ne_u32_e32 vcc, v234, v188
	v_add_u32_e32 v96, 0, v168
	s_nop 0
	v_cndmask_b32_e32 v94, 2.0, v94, vcc
	v_pk_mul_f32 v[90:91], v[94:95], v[90:91]
	s_nop 0
	v_cvt_pk_bf16_f32 v89, v90, v91
	v_add_u32_e32 v90, 0x800, v205
	ds_write2_b64 v90, v[92:93], v[88:89] offset0:64 offset1:144
	v_sub_u32_e32 v90, v232, v190
	v_sub_u32_e32 v88, v229, v190
	v_cvt_f32_i32_e32 v91, v90
	v_cmp_lt_i32_e32 vcc, 0, v88
	v_cvt_f32_i32_e32 v88, v88
	s_nop 0
	v_cndmask_b32_e64 v89, -v231, v230, vcc
	v_cmp_lt_i32_e32 vcc, 0, v90
	v_mul_f32_e32 v88, v89, v88
	v_exp_f32_e32 v88, v88
	v_cndmask_b32_e64 v90, -v231, v230, vcc
	v_mul_f32_e32 v90, v90, v91
	v_exp_f32_e32 v90, v90
	v_cmp_ne_u32_e32 vcc, v232, v181
	s_nop 1
	v_cndmask_b32_e32 v89, 2.0, v90, vcc
	v_cmp_ne_u32_e32 vcc, v229, v190
	v_sub_u32_e32 v90, v233, v190
	v_cvt_f32_i32_e32 v91, v90
	v_cndmask_b32_e32 v88, 2.0, v88, vcc
	v_pk_mul_f32 v[84:85], v[88:89], v[84:85]
	v_sub_u32_e32 v88, v234, v190
	v_cmp_lt_i32_e32 vcc, 0, v88
	v_cvt_f32_i32_e32 v88, v88
	v_cvt_pk_bf16_f32 v84, v84, v85
	v_cndmask_b32_e64 v89, -v231, v230, vcc
	v_cmp_lt_i32_e32 vcc, 0, v90
	v_mul_f32_e32 v88, v89, v88
	v_exp_f32_e32 v88, v88
	v_cndmask_b32_e64 v90, -v231, v230, vcc
	v_mul_f32_e32 v90, v90, v91
	v_exp_f32_e32 v90, v90
	v_cmp_ne_u32_e32 vcc, v233, v181
	s_nop 1
	v_cndmask_b32_e32 v89, 2.0, v90, vcc
	v_cmp_ne_u32_e32 vcc, v234, v190
	s_nop 1
	v_cndmask_b32_e32 v88, 2.0, v88, vcc
	v_pk_mul_f32 v[86:87], v[88:89], v[86:87]
	v_sub_u32_e32 v88, v232, v192
	v_cvt_pk_bf16_f32 v85, v86, v87
	v_sub_u32_e32 v86, v229, v192
	v_cvt_f32_i32_e32 v89, v88
	v_cmp_lt_i32_e32 vcc, 0, v86
	v_cvt_f32_i32_e32 v86, v86
	s_nop 0
	v_cndmask_b32_e64 v87, -v231, v230, vcc
	v_cmp_lt_i32_e32 vcc, 0, v88
	v_mul_f32_e32 v86, v87, v86
	v_exp_f32_e32 v86, v86
	v_cndmask_b32_e64 v88, -v231, v230, vcc
	v_mul_f32_e32 v88, v88, v89
	v_exp_f32_e32 v88, v88
	v_cmp_ne_u32_e32 vcc, v232, v183
	s_nop 1
	v_cndmask_b32_e32 v87, 2.0, v88, vcc
	v_cmp_ne_u32_e32 vcc, v229, v192
	v_sub_u32_e32 v88, v233, v192
	v_cvt_f32_i32_e32 v89, v88
	v_cndmask_b32_e32 v86, 2.0, v86, vcc
	v_pk_mul_f32 v[80:81], v[86:87], v[80:81]
	v_sub_u32_e32 v86, v234, v192
	v_cmp_lt_i32_e32 vcc, 0, v86
	v_cvt_f32_i32_e32 v86, v86
	v_cvt_pk_bf16_f32 v80, v80, v81
	v_cndmask_b32_e64 v87, -v231, v230, vcc
	v_cmp_lt_i32_e32 vcc, 0, v88
	v_mul_f32_e32 v86, v87, v86
	v_exp_f32_e32 v86, v86
	v_cndmask_b32_e64 v88, -v231, v230, vcc
	v_mul_f32_e32 v88, v88, v89
	v_exp_f32_e32 v88, v88
	v_cmp_ne_u32_e32 vcc, v233, v183
	s_nop 1
	v_cndmask_b32_e32 v87, 2.0, v88, vcc
	v_cmp_ne_u32_e32 vcc, v234, v192
	s_nop 1
	v_cndmask_b32_e32 v86, 2.0, v86, vcc
	v_pk_mul_f32 v[82:83], v[86:87], v[82:83]
	s_nop 0
	v_cvt_pk_bf16_f32 v81, v82, v83
	v_add_u32_e32 v82, 0xc00, v205
	ds_write2_b64 v82, v[84:85], v[80:81] offset0:96 offset1:176
	s_waitcnt lgkmcnt(0)
	s_barrier
	s_waitcnt vmcnt(0)
	ds_write_b128 v96, v[0:3]
	ds_write_b128 v207, v[4:7]
	ds_write_b128 v209, v[8:11]
	ds_write_b128 v211, v[12:15]
	ds_read_b64_tr_b16 v[80:81], v212
	ds_read_b64_tr_b16 v[82:83], v212 offset:160
	ds_read_b64_tr_b16 v[86:87], v213 offset:40128
	ds_read_b64_tr_b16 v[84:85], v213 offset:38912
	ds_read_b64_tr_b16 v[88:89], v213 offset:38944
	ds_read_b64_tr_b16 v[90:91], v213 offset:40160
	ds_read_b64_tr_b16 v[92:93], v213 offset:39136
	ds_read_b64_tr_b16 v[96:97], v213 offset:40192
	ds_read_b64_tr_b16 v[94:95], v213 offset:38976
	ds_read_b64_tr_b16 v[98:99], v213 offset:39008
	ds_read_b64_tr_b16 v[102:103], v213 offset:39040
	ds_read_b64_tr_b16 v[106:107], v213 offset:39072
	ds_read_b64_tr_b16 v[100:101], v213 offset:40224
	ds_read_b64_tr_b16 v[104:105], v213 offset:40256
	ds_read_b64_tr_b16 v[108:109], v213 offset:40288
	s_waitcnt lgkmcnt(6)
	v_mfma_f32_16x16x32_bf16 v[110:113], v[80:83], v[94:97], 0
	s_waitcnt lgkmcnt(2)
	v_mfma_f32_16x16x32_bf16 v[96:99], v[80:83], v[98:101], 0
	s_waitcnt lgkmcnt(1)
	v_mfma_f32_16x16x32_bf16 v[100:103], v[80:83], v[102:105], 0
	ds_read_b64_tr_b16 v[104:105], v213 offset:39104
	s_waitcnt lgkmcnt(1)
	v_mfma_f32_16x16x32_bf16 v[114:117], v[80:83], v[106:109], 0
	ds_read_b64_tr_b16 v[106:107], v213 offset:40320
	ds_read_b64_tr_b16 v[94:95], v213 offset:40352
	v_mfma_f32_16x16x32_bf16 v[84:87], v[80:83], v[84:87], 0
	v_mfma_f32_16x16x32_bf16 v[88:91], v[80:83], v[88:91], 0
	s_waitcnt lgkmcnt(1)
	v_mfma_f32_16x16x32_bf16 v[104:107], v[80:83], v[104:107], 0
	s_waitcnt lgkmcnt(0)
	v_mfma_f32_16x16x32_bf16 v[80:83], v[80:83], v[92:95], 0
	ds_read_b64_tr_b16 v[92:93], v212 offset:1280
	ds_read_b64_tr_b16 v[94:95], v212 offset:1440
	ds_read_b64_tr_b16 v[120:121], v213 offset:49856
	ds_read_b64_tr_b16 v[118:119], v213 offset:48640
	ds_read_b64_tr_b16 v[122:123], v213 offset:48672
	ds_read_b64_tr_b16 v[124:125], v213 offset:49888
	ds_read_b64_tr_b16 v[108:109], v213 offset:48864
	s_waitcnt lgkmcnt(3)
	v_mfma_f32_16x16x32_bf16 v[84:87], v[92:95], v[118:121], v[84:87]
	ds_read_b64_tr_b16 v[120:121], v213 offset:49920
	s_waitcnt lgkmcnt(2)
	v_mfma_f32_16x16x32_bf16 v[88:91], v[92:95], v[122:125], v[88:91]
	ds_read_b64_tr_b16 v[118:119], v213 offset:48704
	ds_read_b64_tr_b16 v[122:123], v213 offset:48736
	ds_read_b64_tr_b16 v[126:127], v213 offset:48768
	ds_read_b64_tr_b16 v[130:131], v213 offset:48800
	ds_read_b64_tr_b16 v[124:125], v213 offset:49952
	ds_read_b64_tr_b16 v[128:129], v213 offset:49984
	ds_read_b64_tr_b16 v[132:133], v213 offset:50016
	s_waitcnt lgkmcnt(6)
	v_mfma_f32_16x16x32_bf16 v[118:121], v[92:95], v[118:121], v[110:113]
	s_waitcnt lgkmcnt(2)
	v_mfma_f32_16x16x32_bf16 v[96:99], v[92:95], v[122:125], v[96:99]
	s_nop 0
	ds_read_b64_tr_b16 v[112:113], v213 offset:48832
	s_waitcnt lgkmcnt(1)
	v_mfma_f32_16x16x32_bf16 v[122:125], v[92:95], v[130:133], v[114:117]
	s_nop 2
	ds_read_b64_tr_b16 v[114:115], v213 offset:50048
	ds_read_b64_tr_b16 v[110:111], v213 offset:50080
	v_mfma_f32_16x16x32_bf16 v[100:103], v[92:95], v[126:129], v[100:103]
	s_waitcnt lgkmcnt(1)
	v_mfma_f32_16x16x32_bf16 v[104:107], v[92:95], v[112:115], v[104:107]
	s_waitcnt lgkmcnt(0)
	v_mfma_f32_16x16x32_bf16 v[80:83], v[92:95], v[108:111], v[80:83]
	ds_read_b64_tr_b16 v[92:93], v212 offset:2560
	ds_read_b64_tr_b16 v[94:95], v212 offset:2720
	ds_read_b64_tr_b16 v[110:111], v213 offset:59584
	ds_read_b64_tr_b16 v[108:109], v213 offset:58368
	ds_read_b64_tr_b16 v[112:113], v213 offset:58400
	ds_read_b64_tr_b16 v[114:115], v213 offset:59616
	ds_read_b64_tr_b16 v[116:117], v213 offset:58592
	s_waitcnt lgkmcnt(3)
	v_mfma_f32_16x16x32_bf16 v[84:87], v[92:95], v[108:111], v[84:87]
	ds_read_b64_tr_b16 v[110:111], v213 offset:59648
	s_waitcnt lgkmcnt(2)
	v_mfma_f32_16x16x32_bf16 v[88:91], v[92:95], v[112:115], v[88:91]
	ds_read_b64_tr_b16 v[108:109], v213 offset:58432
	ds_read_b64_tr_b16 v[112:113], v213 offset:58464
	ds_read_b64_tr_b16 v[126:127], v213 offset:58496
	ds_read_b64_tr_b16 v[130:131], v213 offset:58528
	ds_read_b64_tr_b16 v[114:115], v213 offset:59680
	ds_read_b64_tr_b16 v[128:129], v213 offset:59712
	ds_read_b64_tr_b16 v[132:133], v213 offset:59744
	s_waitcnt lgkmcnt(6)
	v_mfma_f32_16x16x32_bf16 v[134:137], v[92:95], v[108:111], v[118:121]
	s_waitcnt lgkmcnt(2)
	v_mfma_f32_16x16x32_bf16 v[112:115], v[92:95], v[112:115], v[96:99]
	s_nop 2
	ds_read_b64_tr_b16 v[96:97], v213 offset:58560
	ds_read_b64_tr_b16 v[98:99], v213 offset:59776
	ds_read_b64_tr_b16 v[118:119], v213 offset:59808
	s_waitcnt lgkmcnt(4)
	v_mfma_f32_16x16x32_bf16 v[126:129], v[92:95], v[126:129], v[100:103]
	s_waitcnt lgkmcnt(3)
	v_mfma_f32_16x16x32_bf16 v[120:123], v[92:95], v[130:133], v[122:125]
	s_waitcnt lgkmcnt(1)
	v_mfma_f32_16x16x32_bf16 v[130:133], v[92:95], v[96:99], v[104:107]
	s_waitcnt lgkmcnt(0)
	v_mfma_f32_16x16x32_bf16 v[116:119], v[92:95], v[116:119], v[80:83]
	ds_read_b64_tr_b16 v[138:139], v212 offset:3840
	ds_read_b64_tr_b16 v[140:141], v212 offset:4000
	s_nop 0
	ds_read_b64_tr_b16 v[82:83], v214 offset:59584
	ds_read_b64_tr_b16 v[80:81], v214 offset:58368
	ds_read_b64_tr_b16 v[92:93], v214 offset:58400
	ds_read_b64_tr_b16 v[94:95], v214 offset:59616
	ds_read_b64_tr_b16 v[124:125], v214 offset:58592
	s_waitcnt lgkmcnt(3)
	v_mfma_f32_16x16x32_bf16 v[108:111], v[138:141], v[80:83], v[84:87]
	ds_read_b64_tr_b16 v[82:83], v214 offset:59648
	s_waitcnt lgkmcnt(2)
	v_mfma_f32_16x16x32_bf16 v[104:107], v[138:141], v[92:95], v[88:91]
	ds_read_b64_tr_b16 v[80:81], v214 offset:58432
	ds_read_b64_tr_b16 v[84:85], v214 offset:58464
	s_nop 0
	ds_read_b64_tr_b16 v[88:89], v214 offset:58496
	ds_read_b64_tr_b16 v[92:93], v214 offset:58528
	ds_read_b64_tr_b16 v[86:87], v214 offset:59680
	ds_read_b64_tr_b16 v[90:91], v214 offset:59712
	ds_read_b64_tr_b16 v[94:95], v214 offset:59744
	s_waitcnt lgkmcnt(6)
	v_mfma_f32_16x16x32_bf16 v[96:99], v[138:141], v[80:83], v[134:137]
	ds_read_b64_tr_b16 v[80:81], v214 offset:58560
	s_waitcnt lgkmcnt(2)
	v_mfma_f32_16x16x32_bf16 v[88:91], v[138:141], v[88:91], v[126:129]
	ds_read_b64_tr_b16 v[82:83], v214 offset:59776
	s_nop 1
	ds_read_b64_tr_b16 v[126:127], v214 offset:59808
	v_mfma_f32_16x16x32_bf16 v[100:103], v[138:141], v[84:87], v[112:115]
	s_waitcnt lgkmcnt(3)
	v_mfma_f32_16x16x32_bf16 v[92:95], v[138:141], v[92:95], v[120:123]
	s_waitcnt lgkmcnt(1)
	v_mfma_f32_16x16x32_bf16 v[80:83], v[138:141], v[80:83], v[130:133]
	s_waitcnt lgkmcnt(0)
	v_mfma_f32_16x16x32_bf16 v[84:87], v[138:141], v[124:127], v[116:119]
	v_add_u32_e32 v112, s42, v187
	ds_read_b128 v[112:115], v112
	v_add_u32_e32 v199, 0, v187
	v_add_u32_e32 v116, 0x13400, v199
	ds_read_b128 v[116:119], v116
	v_add_u32_e32 v120, 0x13800, v199
	s_waitcnt lgkmcnt(1)
	v_mfma_f32_16x16x32_bf16 v[112:115], v[44:47], v[112:115], 0
	s_waitcnt lgkmcnt(0)
	v_mfma_f32_16x16x32_bf16 v[112:115], v[48:51], v[116:119], v[112:115]
	ds_read_b128 v[116:119], v120
	v_add_u32_e32 v120, 0x13c00, v199
	ds_read_b128 v[120:123], v120
	s_waitcnt lgkmcnt(1)
	v_mfma_f32_16x16x32_bf16 v[112:115], v[52:55], v[116:119], v[112:115]
	v_add_u32_e32 v116, 0x14000, v199
	s_waitcnt lgkmcnt(0)
	v_mfma_f32_16x16x32_bf16 v[136:139], v[60:63], v[120:123], v[112:115]
	v_add_u32_e32 v120, 0x14800, v199
	s_nop 3
	ds_read_b128 v[112:115], v116
	v_add_u32_e32 v116, 0x14400, v199
	ds_read_b128 v[116:119], v116
	s_waitcnt lgkmcnt(1)
	v_mfma_f32_16x16x32_bf16 v[112:115], v[44:47], v[112:115], 0
	s_waitcnt lgkmcnt(0)
	v_mfma_f32_16x16x32_bf16 v[112:115], v[48:51], v[116:119], v[112:115]
	ds_read_b128 v[116:119], v120
	v_add_u32_e32 v120, 0x14c00, v199
	s_waitcnt lgkmcnt(0)
	v_mfma_f32_16x16x32_bf16 v[112:115], v[52:55], v[116:119], v[112:115]
	ds_read_b128 v[116:119], v120
	s_waitcnt lgkmcnt(0)
	v_mfma_f32_16x16x32_bf16 v[140:143], v[60:63], v[116:119], v[112:115]
	s_nop 4
	v_add_u32_e32 v112, 0x15000, v199
	ds_read_b128 v[112:115], v112
	v_add_u32_e32 v116, 0x15400, v199
	ds_read_b128 v[116:119], v116
	v_add_u32_e32 v120, 0x15800, v199
	s_waitcnt lgkmcnt(1)
	v_mfma_f32_16x16x32_bf16 v[112:115], v[44:47], v[112:115], 0
	s_waitcnt lgkmcnt(0)
	v_mfma_f32_16x16x32_bf16 v[112:115], v[48:51], v[116:119], v[112:115]
	ds_read_b128 v[116:119], v120
	v_add_u32_e32 v120, 0x15c00, v199
	ds_read_b128 v[120:123], v120
	s_waitcnt lgkmcnt(1)
	v_mfma_f32_16x16x32_bf16 v[112:115], v[52:55], v[116:119], v[112:115]
	v_add_u32_e32 v116, 0x16000, v199
	s_waitcnt lgkmcnt(0)
	v_mfma_f32_16x16x32_bf16 v[124:127], v[60:63], v[120:123], v[112:115]
	v_add_u32_e32 v120, 0x16800, v199
	s_nop 3
	ds_read_b128 v[112:115], v116
	v_add_u32_e32 v116, 0x16400, v199
	ds_read_b128 v[116:119], v116
	s_waitcnt lgkmcnt(1)
	v_mfma_f32_16x16x32_bf16 v[112:115], v[44:47], v[112:115], 0
	s_waitcnt lgkmcnt(0)
	v_mfma_f32_16x16x32_bf16 v[112:115], v[48:51], v[116:119], v[112:115]
	ds_read_b128 v[116:119], v120
	v_add_u32_e32 v120, 0x16c00, v199
	s_waitcnt lgkmcnt(0)
	v_mfma_f32_16x16x32_bf16 v[112:115], v[52:55], v[116:119], v[112:115]
	ds_read_b128 v[116:119], v120
	s_waitcnt lgkmcnt(0)
	v_mfma_f32_16x16x32_bf16 v[132:135], v[60:63], v[116:119], v[112:115]
	s_nop 4
	v_add_u32_e32 v112, 0x17000, v199
	ds_read_b128 v[112:115], v112
	v_add_u32_e32 v116, 0x17400, v199
	ds_read_b128 v[116:119], v116
	v_add_u32_e32 v120, 0x17800, v199
	v_add_u32_e32 v128, 0x18000, v199
	s_waitcnt lgkmcnt(1)
	v_mfma_f32_16x16x32_bf16 v[112:115], v[44:47], v[112:115], 0
	s_waitcnt lgkmcnt(0)
	v_mfma_f32_16x16x32_bf16 v[112:115], v[48:51], v[116:119], v[112:115]
	ds_read_b128 v[116:119], v120
	v_add_u32_e32 v120, 0x17c00, v199
	ds_read_b128 v[120:123], v120
	s_waitcnt lgkmcnt(1)
	v_mfma_f32_16x16x32_bf16 v[112:115], v[52:55], v[116:119], v[112:115]
	s_waitcnt lgkmcnt(0)
	v_mfma_f32_16x16x32_bf16 v[116:119], v[60:63], v[120:123], v[112:115]
	v_add_u32_e32 v120, 0x18400, v199
	ds_read_b128 v[120:123], v120
	s_nop 3
	ds_read_b128 v[112:115], v128
	s_waitcnt lgkmcnt(0)
	v_mfma_f32_16x16x32_bf16 v[112:115], v[44:47], v[112:115], 0
	v_add_u32_e32 v128, 0x18800, v199
	v_mfma_f32_16x16x32_bf16 v[112:115], v[48:51], v[120:123], v[112:115]
	ds_read_b128 v[120:123], v128
	v_add_u32_e32 v128, 0x18c00, v199
	s_waitcnt lgkmcnt(0)
	v_mfma_f32_16x16x32_bf16 v[112:115], v[52:55], v[120:123], v[112:115]
	ds_read_b128 v[120:123], v128
	s_waitcnt lgkmcnt(0)
	v_mfma_f32_16x16x32_bf16 v[128:131], v[60:63], v[120:123], v[112:115]
	s_nop 4
	v_add_u32_e32 v112, 0x19000, v199
	ds_read_b128 v[112:115], v112
	v_add_u32_e32 v120, 0x19400, v199
	ds_read_b128 v[120:123], v120
	v_add_u32_e32 v144, 0x19800, v199
	v_add_u32_e32 v148, 0x1a800, v199
	s_waitcnt lgkmcnt(1)
	v_mfma_f32_16x16x32_bf16 v[112:115], v[44:47], v[112:115], 0
	s_waitcnt lgkmcnt(0)
	v_mfma_f32_16x16x32_bf16 v[112:115], v[48:51], v[120:123], v[112:115]
	ds_read_b128 v[120:123], v144
	v_add_u32_e32 v144, 0x19c00, v199
	ds_read_b128 v[144:147], v144
	s_waitcnt lgkmcnt(1)
	v_mfma_f32_16x16x32_bf16 v[112:115], v[52:55], v[120:123], v[112:115]
	v_add_u32_e32 v120, 0x1a000, v199
	ds_read_b128 v[120:123], v120
	s_waitcnt lgkmcnt(1)
	v_mfma_f32_16x16x32_bf16 v[112:115], v[60:63], v[144:147], v[112:115]
	v_add_u32_e32 v144, 0x1a400, v199
	ds_read_b128 v[144:147], v144
	s_waitcnt lgkmcnt(1)
	v_mfma_f32_16x16x32_bf16 v[120:123], v[44:47], v[120:123], 0
	s_waitcnt lgkmcnt(0)
	v_mfma_f32_16x16x32_bf16 v[120:123], v[48:51], v[144:147], v[120:123]
	ds_read_b128 v[144:147], v148
	v_add_u32_e32 v148, 0x1ac00, v199
	s_waitcnt lgkmcnt(0)
	v_mfma_f32_16x16x32_bf16 v[120:123], v[52:55], v[144:147], v[120:123]
	ds_read_b128 v[144:147], v148
	s_waitcnt lgkmcnt(0)
	v_mfma_f32_16x16x32_bf16 v[120:123], v[60:63], v[144:147], v[120:123]
	s_waitcnt lgkmcnt(0)
	s_barrier
	ds_write_b128 v220, v[64:67]
	ds_write_b128 v221, v[68:71]
	ds_write_b128 v221, v[72:75] offset:8704
	ds_write_b128 v221, v[76:79] offset:17408
	ds_read_b128 v[64:67], v199
	ds_read_b128 v[68:71], v199 offset:1024
	s_waitcnt lgkmcnt(1)
	v_mfma_f32_16x16x32_bf16 v[64:67], v[44:47], v[64:67], 0
	s_waitcnt lgkmcnt(0)
	v_mfma_f32_16x16x32_bf16 v[64:67], v[48:51], v[68:71], v[64:67]
	ds_read_b128 v[68:71], v199 offset:2048
	ds_read_b128 v[72:75], v199 offset:3072
	s_waitcnt lgkmcnt(1)
	v_mfma_f32_16x16x32_bf16 v[64:67], v[52:55], v[68:71], v[64:67]
	ds_read_b128 v[68:71], v199 offset:5120
	s_waitcnt lgkmcnt(1)
	v_mfma_f32_16x16x32_bf16 v[152:155], v[60:63], v[72:75], v[64:67]
	s_nop 4
	ds_read_b128 v[64:67], v199 offset:4096
	s_waitcnt lgkmcnt(0)
	v_mfma_f32_16x16x32_bf16 v[64:67], v[44:47], v[64:67], 0
	v_mfma_f32_16x16x32_bf16 v[64:67], v[48:51], v[68:71], v[64:67]
	ds_read_b128 v[68:71], v199 offset:6144
	s_waitcnt lgkmcnt(0)
	v_mfma_f32_16x16x32_bf16 v[64:67], v[52:55], v[68:71], v[64:67]
	ds_read_b128 v[68:71], v199 offset:7168
	s_waitcnt lgkmcnt(0)
	v_mfma_f32_16x16x32_bf16 v[156:159], v[60:63], v[68:71], v[64:67]
	s_nop 4
	ds_read_b128 v[64:67], v199 offset:8192
	ds_read_b128 v[68:71], v199 offset:9216
	s_waitcnt lgkmcnt(1)
	v_mfma_f32_16x16x32_bf16 v[64:67], v[44:47], v[64:67], 0
	s_waitcnt lgkmcnt(0)
	v_mfma_f32_16x16x32_bf16 v[64:67], v[48:51], v[68:71], v[64:67]
	ds_read_b128 v[68:71], v199 offset:10240
	ds_read_b128 v[72:75], v199 offset:11264
	s_waitcnt lgkmcnt(1)
	v_mfma_f32_16x16x32_bf16 v[64:67], v[52:55], v[68:71], v[64:67]
	ds_read_b128 v[68:71], v199 offset:13312
	s_waitcnt lgkmcnt(1)
	v_mfma_f32_16x16x32_bf16 v[144:147], v[60:63], v[72:75], v[64:67]
	s_nop 4
	ds_read_b128 v[64:67], v199 offset:12288
	s_waitcnt lgkmcnt(0)
	v_mfma_f32_16x16x32_bf16 v[64:67], v[44:47], v[64:67], 0
	v_mfma_f32_16x16x32_bf16 v[64:67], v[48:51], v[68:71], v[64:67]
	ds_read_b128 v[68:71], v199 offset:14336
	s_waitcnt lgkmcnt(0)
	v_mfma_f32_16x16x32_bf16 v[64:67], v[52:55], v[68:71], v[64:67]
	ds_read_b128 v[68:71], v199 offset:15360
	s_waitcnt lgkmcnt(0)
	v_mfma_f32_16x16x32_bf16 v[148:151], v[60:63], v[68:71], v[64:67]
	s_nop 4
	ds_read_b128 v[64:67], v199 offset:16384
	ds_read_b128 v[68:71], v199 offset:17408
	s_waitcnt lgkmcnt(1)
	v_mfma_f32_16x16x32_bf16 v[64:67], v[44:47], v[64:67], 0
	s_waitcnt lgkmcnt(0)
	v_mfma_f32_16x16x32_bf16 v[64:67], v[48:51], v[68:71], v[64:67]
	ds_read_b128 v[68:71], v199 offset:18432
	ds_read_b128 v[72:75], v199 offset:19456
	s_waitcnt lgkmcnt(1)
	v_mfma_f32_16x16x32_bf16 v[64:67], v[52:55], v[68:71], v[64:67]
	ds_read_b128 v[68:71], v199 offset:21504
	s_waitcnt lgkmcnt(1)
	v_mfma_f32_16x16x32_bf16 v[72:75], v[60:63], v[72:75], v[64:67]
	s_nop 4
	ds_read_b128 v[64:67], v199 offset:20480
	s_waitcnt lgkmcnt(0)
	v_mfma_f32_16x16x32_bf16 v[64:67], v[44:47], v[64:67], 0
	v_mfma_f32_16x16x32_bf16 v[64:67], v[48:51], v[68:71], v[64:67]
	ds_read_b128 v[68:71], v199 offset:22528
	s_waitcnt lgkmcnt(0)
	v_mfma_f32_16x16x32_bf16 v[64:67], v[52:55], v[68:71], v[64:67]
	ds_read_b128 v[68:71], v199 offset:23552
	s_waitcnt lgkmcnt(0)
	v_mfma_f32_16x16x32_bf16 v[76:79], v[60:63], v[68:71], v[64:67]
	s_nop 4
	ds_read_b128 v[64:67], v199 offset:24576
	ds_read_b128 v[68:71], v199 offset:25600
	s_waitcnt lgkmcnt(1)
	v_mfma_f32_16x16x32_bf16 v[64:67], v[44:47], v[64:67], 0
	s_waitcnt lgkmcnt(0)
	v_mfma_f32_16x16x32_bf16 v[64:67], v[48:51], v[68:71], v[64:67]
	ds_read_b128 v[68:71], v199 offset:26624
	ds_read_b128 v[236:239], v199 offset:27648
	s_waitcnt lgkmcnt(1)
	v_mfma_f32_16x16x32_bf16 v[64:67], v[52:55], v[68:71], v[64:67]
	ds_read_b128 v[68:71], v199 offset:28672
	s_waitcnt lgkmcnt(1)
	v_mfma_f32_16x16x32_bf16 v[64:67], v[60:63], v[236:239], v[64:67]
	ds_read_b128 v[236:239], v199 offset:29696
	s_waitcnt lgkmcnt(1)
	v_mfma_f32_16x16x32_bf16 v[68:71], v[44:47], v[68:71], 0
	s_waitcnt lgkmcnt(0)
	v_mfma_f32_16x16x32_bf16 v[68:71], v[48:51], v[236:239], v[68:71]
	ds_read_b128 v[236:239], v199 offset:30720
	s_waitcnt lgkmcnt(0)
	v_mfma_f32_16x16x32_bf16 v[68:71], v[52:55], v[236:239], v[68:71]
	ds_read_b128 v[236:239], v199 offset:31744
	s_waitcnt lgkmcnt(0)
	v_mfma_f32_16x16x32_bf16 v[68:71], v[60:63], v[236:239], v[68:71]
	s_add_i32 s45, s45, s34
	s_cmpk_gt_i32 s45, 0x3ff
	s_cselect_b64 s[16:17], -1, 0
	s_and_b64 vcc, exec, s[16:17]
	s_cbranch_vccnz .LBB0_902
	s_bfe_u32 s98, s45, 0x20005
	s_lshl_b32 s98, s98, 2
	v_mov_b32_e32 v241, s98
	global_load_dword v242, v241, s[54:55]
	global_load_dword v243, v241, s[54:55] offset:16
	s_ashr_i32 s48, s45, 7
	s_and_b32 s64, s45, 31
	s_ashr_i32 s49, s48, 31
	s_lshl_b64 s[52:53], s[48:49], 12
	s_lshl_b32 s4, s64, 7
	s_or_b32 s52, s52, s4
	s_mul_i32 s4, s53, 0x1c00
	s_mul_hi_u32 s49, s52, 0x1c00
	s_bfe_u32 s47, s45, 0x20005
	s_add_i32 s49, s49, s4
	s_mul_i32 s4, s52, 0x1c00
	s_add_u32 s62, s0, s4
	s_addc_u32 s49, s1, s49
	s_lshl_b32 s4, s47, 8
	s_add_u32 s62, s62, s4
	s_addc_u32 s63, s49, 0
	s_lshl_b32 s48, s48, 2
	s_ashr_i32 s49, s48, 31
	s_or_b32 s48, s48, s47
	s_lshl_b64 s[48:49], s[48:49], 20
	s_add_u32 s47, s11, s48
	s_addc_u32 s49, s13, s49
	s_lshl_b32 s48, s64, 15
	s_add_u32 s48, s47, s48
	s_addc_u32 s49, s49, 0
	v_mov_b32_e32 v199, v167
	v_lshl_add_u64 v[40:41], s[48:49], 0, v[198:199]
	v_add_co_u32_e32 v16, vcc, s28, v40
	v_lshl_add_u64 v[42:43], s[52:53], 0, v[170:171]
	s_nop 0
	v_addc_co_u32_e32 v17, vcc, 0, v41, vcc
	v_mov_b64_e32 v[44:45], s[0:1]
	v_add_co_u32_e32 v28, vcc, s30, v40
	v_mad_u64_u32 v[44:45], s[52:53], v42, s26, v[44:45]
	v_lshl_add_u64 v[8:9], s[62:63], 0, v[166:167]
	v_addc_co_u32_e32 v29, vcc, 0, v41, vcc
	v_mad_i32_i24 v45, v43, s26, v45
	v_lshl_add_u64 v[32:33], v[8:9], 0, v[196:197]
	v_add_co_u32_e32 v40, vcc, s31, v40
	v_lshl_add_u64 v[42:43], v[44:45], 0, s[4:5]
	v_mov_b32_e32 v201, v167
	v_lshl_add_u64 v[4:5], v[8:9], 0, v[194:195]
	v_lshl_add_u64 v[24:25], v[32:33], 0, s[6:7]
	v_lshl_add_u64 v[36:37], v[32:33], 0, s[8:9]
	v_addc_co_u32_e32 v41, vcc, 0, v41, vcc
	v_lshl_add_u64 v[60:61], v[42:43], 0, v[200:201]
	global_load_dwordx4 v[0:3], v[4:5], off offset:1024
	s_nop 0
	global_load_dwordx4 v[4:7], v[4:5], off offset:2048
	s_nop 0
	global_load_dwordx4 v[8:11], v[32:33], off offset:1024
	global_load_dwordx4 v[12:15], v[32:33], off offset:2048
	s_nop 0
	global_load_dwordx4 v[16:19], v[16:17], off
	s_nop 0
	global_load_dwordx4 v[20:23], v[24:25], off offset:1024
	s_nop 0
	global_load_dwordx4 v[24:27], v[24:25], off offset:2048
	s_nop 0
	global_load_dwordx4 v[28:31], v[28:29], off
	s_nop 0
	global_load_dwordx4 v[32:35], v[36:37], off offset:1024
	s_nop 0
	global_load_dwordx4 v[36:39], v[36:37], off offset:2048
	s_nop 0
	global_load_dwordx4 v[40:43], v[40:41], off
	s_nop 0
	global_load_dwordx4 v[44:47], v[60:61], off
	global_load_dwordx4 v[48:51], v[60:61], off offset:64
	global_load_dwordx4 v[52:55], v[60:61], off offset:128
	global_load_dwordx4 v[56:59], v198, s[48:49]
	s_nop 0
	global_load_dwordx4 v[60:63], v[60:61], off offset:192
	s_branch .LBB0_902

	.amdhsa_kernel _Z10fwd_kernel6Paramsiii
		.amdhsa_group_segment_fixed_size 0
		.amdhsa_private_segment_fixed_size 0
		.amdhsa_kernarg_size 504
		.amdhsa_user_sgpr_count 2
		.amdhsa_user_sgpr_dispatch_ptr 0
		.amdhsa_user_sgpr_queue_ptr 0
		.amdhsa_user_sgpr_kernarg_segment_ptr 1
		.amdhsa_user_sgpr_dispatch_id 0
		.amdhsa_user_sgpr_kernarg_preload_length 0
		.amdhsa_user_sgpr_kernarg_preload_offset 0
		.amdhsa_user_sgpr_private_segment_size 0
		.amdhsa_uses_dynamic_stack 0
		.amdhsa_enable_private_segment 0
		.amdhsa_system_sgpr_workgroup_id_x 1
		.amdhsa_system_sgpr_workgroup_id_y 0
		.amdhsa_system_sgpr_workgroup_id_z 0
		.amdhsa_system_sgpr_workgroup_info 0
		.amdhsa_system_vgpr_workitem_id 2
		.amdhsa_next_free_vgpr 256
		.amdhsa_next_free_sgpr 102
		.amdhsa_accum_offset 256
		.amdhsa_reserve_vcc 1
		.amdhsa_float_round_mode_32 0
		.amdhsa_float_round_mode_16_64 0
		.amdhsa_float_denorm_mode_32 3
		.amdhsa_float_denorm_mode_16_64 3
		.amdhsa_dx10_clamp 1
		.amdhsa_ieee_mode 1
		.amdhsa_fp16_overflow 0
		.amdhsa_tg_split 0
		.amdhsa_exception_fp_ieee_invalid_op 0
		.amdhsa_exception_fp_denorm_src 0
		.amdhsa_exception_fp_ieee_div_zero 0
		.amdhsa_exception_fp_ieee_overflow 0
		.amdhsa_exception_fp_ieee_underflow 0
		.amdhsa_exception_fp_ieee_inexact 0
		.amdhsa_exception_int_div_zero 0
	.end_amdhsa_kernel

amdhsa.kernels:
  - .agpr_count:     0
    .args:
      - .offset:         0
        .size:           232
        .value_kind:     by_value
      - .offset:         232
        .size:           4
        .value_kind:     by_value
      - .offset:         236
        .size:           4
        .value_kind:     by_value
      - .offset:         240
        .size:           4
        .value_kind:     by_value
      - .offset:         248
        .size:           4
        .value_kind:     hidden_block_count_x
      - .offset:         252
        .size:           4
        .value_kind:     hidden_block_count_y
      - .offset:         256
        .size:           4
        .value_kind:     hidden_block_count_z
      - .offset:         260
        .size:           2
        .value_kind:     hidden_group_size_x
      - .offset:         262
        .size:           2
        .value_kind:     hidden_group_size_y
      - .offset:         264
        .size:           2
        .value_kind:     hidden_group_size_z
      - .offset:         266
        .size:           2
        .value_kind:     hidden_remainder_x
      - .offset:         268
        .size:           2
        .value_kind:     hidden_remainder_y
      - .offset:         270
        .size:           2
        .value_kind:     hidden_remainder_z
      - .offset:         288
        .size:           8
        .value_kind:     hidden_global_offset_x
      - .offset:         296
        .size:           8
        .value_kind:     hidden_global_offset_y
      - .offset:         304
        .size:           8
        .value_kind:     hidden_global_offset_z
      - .offset:         312
        .size:           2
        .value_kind:     hidden_grid_dims
      - .offset:         336
        .size:           8
        .value_kind:     hidden_multigrid_sync_arg
      - .offset:         368
        .size:           4
        .value_kind:     hidden_dynamic_lds_size
    .group_segment_fixed_size: 0
    .kernarg_segment_align: 8
    .kernarg_segment_size: 504
    .language:       OpenCL C
    .language_version:
      - 2
      - 0
    .max_flat_workgroup_size: 512
    .name:           _Z10fwd_kernel6Paramsiii
    .private_segment_fixed_size: 0
    .sgpr_count:     108
    .sgpr_spill_count: 42
    .symbol:         _Z10fwd_kernel6Paramsiii.kd
    .uniform_work_group_size: 1
    .uses_dynamic_stack: false
    .vgpr_count:     256
    .vgpr_spill_count: 0
    .wavefront_size: 64
